# e17: P0 W1 weight conversion loads 32-deep with masked lanes zero-filled (on top of e14+e15)
# speedup vs baseline: 1.0032x; 1.0032x over previous
.Le17_rd:
	s_waitcnt lgkmcnt(0)
	v_add_u32_e32 v78, s8, v69
	ds_read2_b32 v[10:11], v70 offset1:33
	s_ashr_i32 s5, s4, 31
	v_ashrrev_i32_e32 v79, 31, v78
	s_waitcnt lgkmcnt(0)
	v_cvt_pk_bf16_f32 v10, v10, v11
	ds_read2_b32 v[12:13], v70 offset0:66 offset1:99
	v_lshl_add_u64 v[80:81], s[4:5], 1, v[8:9]
	v_lshlrev_b64 v[82:83], 13, v[78:79]
	s_waitcnt lgkmcnt(0)
	v_cvt_pk_bf16_f32 v11, v12, v13
	ds_read2_b32 v[12:13], v70 offset0:132 offset1:165
	v_lshl_add_u64 v[82:83], v[80:81], 0, v[82:83]
	s_waitcnt lgkmcnt(0)
	v_cvt_pk_bf16_f32 v12, v12, v13
	ds_read2_b32 v[76:77], v70 offset0:198 offset1:231
	s_waitcnt lgkmcnt(0)
	v_cvt_pk_bf16_f32 v13, v76, v77
	global_store_dwordx4 v[82:83], v[10:13], off
	v_add_u32_e32 v82, 8, v78
	v_ashrrev_i32_e32 v83, 31, v82
	ds_read2_b32 v[76:77], v70 offset0:8 offset1:41
	s_waitcnt lgkmcnt(0)
	v_cvt_pk_bf16_f32 v10, v76, v77
	ds_read2_b32 v[12:13], v70 offset0:74 offset1:107
	v_lshlrev_b64 v[82:83], 13, v[82:83]
	s_waitcnt lgkmcnt(0)
	v_cvt_pk_bf16_f32 v11, v12, v13
	ds_read2_b32 v[12:13], v70 offset0:140 offset1:173
	v_lshl_add_u64 v[82:83], v[80:81], 0, v[82:83]
	s_waitcnt lgkmcnt(0)
	v_cvt_pk_bf16_f32 v12, v12, v13
	ds_read2_b32 v[76:77], v70 offset0:206 offset1:239
	s_waitcnt lgkmcnt(0)
	v_cvt_pk_bf16_f32 v13, v76, v77
	global_store_dwordx4 v[82:83], v[10:13], off
	v_add_u32_e32 v82, 16, v78
	ds_read2_b32 v[76:77], v70 offset0:16 offset1:49
	s_waitcnt lgkmcnt(0)
	v_cvt_pk_bf16_f32 v10, v76, v77
	ds_read2_b32 v[12:13], v70 offset0:82 offset1:115
	v_ashrrev_i32_e32 v83, 31, v82
	s_waitcnt lgkmcnt(0)
	v_cvt_pk_bf16_f32 v11, v12, v13
	ds_read2_b32 v[12:13], v70 offset0:148 offset1:181
	v_lshlrev_b64 v[82:83], 13, v[82:83]
	s_waitcnt lgkmcnt(0)
	v_cvt_pk_bf16_f32 v12, v12, v13
	ds_read2_b32 v[76:77], v70 offset0:214 offset1:247
	s_waitcnt lgkmcnt(0)
	v_cvt_pk_bf16_f32 v13, v76, v77
	v_lshl_add_u64 v[82:83], v[80:81], 0, v[82:83]
	ds_read2_b32 v[76:77], v70 offset0:24 offset1:57
	global_store_dwordx4 v[82:83], v[10:13], off
	v_add_u32_e32 v78, 24, v78
	v_ashrrev_i32_e32 v79, 31, v78
	s_waitcnt lgkmcnt(0)
	v_cvt_pk_bf16_f32 v10, v76, v77
	ds_read2_b32 v[12:13], v70 offset0:90 offset1:123
	s_waitcnt lgkmcnt(0)
	v_cvt_pk_bf16_f32 v11, v12, v13
	ds_read2_b32 v[12:13], v70 offset0:156 offset1:189
	s_waitcnt lgkmcnt(0)
	v_cvt_pk_bf16_f32 v12, v12, v13
	ds_read2_b32 v[76:77], v70 offset0:222 offset1:255
	v_lshlrev_b64 v[78:79], 13, v[78:79]
	s_waitcnt lgkmcnt(0)
	v_cvt_pk_bf16_f32 v13, v76, v77
	v_lshl_add_u64 v[76:77], v[80:81], 0, v[78:79]
	global_store_dwordx4 v[76:77], v[10:13], off
	s_waitcnt lgkmcnt(0)

.LBB0_115:
	s_andn2_saveexec_b64 s[4:5], s[4:5]
	s_and_b32 s6, s8, 0xffffff80
	v_bfe_u32 v2, v2, 1, 6
	v_and_b32_e32 v10, 64, v75
	v_or3_b32 v2, v2, s6, v10
	s_or_b64 exec, exec, s[4:5]
	v_cmp_gt_i32_e32 vcc, 0, v2
	s_lshl_b32 s4, s16, 6
	v_add_u32_e32 v197, v15, v16
	v_or_b32_e32 v196, s4, v14
	v_mul_u32_u24_e32 v196, 0x8900, v196
	v_lshl_add_u32 v196, v2, 2, v196
	v_mov_b32_e32 v164, 0
	v_mov_b32_e32 v165, 0
	v_mov_b32_e32 v166, 0
	v_mov_b32_e32 v167, 0
	v_mov_b32_e32 v168, 0
	v_mov_b32_e32 v169, 0
	v_mov_b32_e32 v170, 0
	v_mov_b32_e32 v171, 0
	v_mov_b32_e32 v172, 0
	v_mov_b32_e32 v173, 0
	v_mov_b32_e32 v174, 0
	v_mov_b32_e32 v175, 0
	v_mov_b32_e32 v176, 0
	v_mov_b32_e32 v177, 0
	v_mov_b32_e32 v178, 0
	v_mov_b32_e32 v179, 0
	v_mov_b32_e32 v180, 0
	v_mov_b32_e32 v181, 0
	v_mov_b32_e32 v182, 0
	v_mov_b32_e32 v183, 0
	v_mov_b32_e32 v184, 0
	v_mov_b32_e32 v185, 0
	v_mov_b32_e32 v186, 0
	v_mov_b32_e32 v187, 0
	v_mov_b32_e32 v188, 0
	v_mov_b32_e32 v189, 0
	v_mov_b32_e32 v190, 0
	v_mov_b32_e32 v191, 0
	v_mov_b32_e32 v192, 0
	v_mov_b32_e32 v193, 0
	v_mov_b32_e32 v194, 0
	v_mov_b32_e32 v195, 0
	s_mov_b64 s[6:7], exec
	s_andn2_b64 exec, exec, vcc
	s_cbranch_execz .Le17_wr
	global_load_dword v164, v196, s[50:51] nt
	v_add_u32_e32 v196, 0x11200, v196
	global_load_dword v165, v196, s[50:51] nt
	v_add_u32_e32 v196, 0x11200, v196
	global_load_dword v166, v196, s[50:51] nt
	v_add_u32_e32 v196, 0x11200, v196
	global_load_dword v167, v196, s[50:51] nt
	v_add_u32_e32 v196, 0x11200, v196
	global_load_dword v168, v196, s[50:51] nt
	v_add_u32_e32 v196, 0x11200, v196
	global_load_dword v169, v196, s[50:51] nt
	v_add_u32_e32 v196, 0x11200, v196
	global_load_dword v170, v196, s[50:51] nt
	v_add_u32_e32 v196, 0x11200, v196
	global_load_dword v171, v196, s[50:51] nt
	v_add_u32_e32 v196, 0x11200, v196
	global_load_dword v172, v196, s[50:51] nt
	v_add_u32_e32 v196, 0x11200, v196
	global_load_dword v173, v196, s[50:51] nt
	v_add_u32_e32 v196, 0x11200, v196
	global_load_dword v174, v196, s[50:51] nt
	v_add_u32_e32 v196, 0x11200, v196
	global_load_dword v175, v196, s[50:51] nt
	v_add_u32_e32 v196, 0x11200, v196
	global_load_dword v176, v196, s[50:51] nt
	v_add_u32_e32 v196, 0x11200, v196
	global_load_dword v177, v196, s[50:51] nt
	v_add_u32_e32 v196, 0x11200, v196
	global_load_dword v178, v196, s[50:51] nt
	v_add_u32_e32 v196, 0x11200, v196
	global_load_dword v179, v196, s[50:51] nt
	v_add_u32_e32 v196, 0x11200, v196
	global_load_dword v180, v196, s[50:51] nt
	v_add_u32_e32 v196, 0x11200, v196
	global_load_dword v181, v196, s[50:51] nt
	v_add_u32_e32 v196, 0x11200, v196
	global_load_dword v182, v196, s[50:51] nt
	v_add_u32_e32 v196, 0x11200, v196
	global_load_dword v183, v196, s[50:51] nt
	v_add_u32_e32 v196, 0x11200, v196
	global_load_dword v184, v196, s[50:51] nt
	v_add_u32_e32 v196, 0x11200, v196
	global_load_dword v185, v196, s[50:51] nt
	v_add_u32_e32 v196, 0x11200, v196
	global_load_dword v186, v196, s[50:51] nt
	v_add_u32_e32 v196, 0x11200, v196
	global_load_dword v187, v196, s[50:51] nt
	v_add_u32_e32 v196, 0x11200, v196
	global_load_dword v188, v196, s[50:51] nt
	v_add_u32_e32 v196, 0x11200, v196
	global_load_dword v189, v196, s[50:51] nt
	v_add_u32_e32 v196, 0x11200, v196
	global_load_dword v190, v196, s[50:51] nt
	v_add_u32_e32 v196, 0x11200, v196
	global_load_dword v191, v196, s[50:51] nt
	v_add_u32_e32 v196, 0x11200, v196
	global_load_dword v192, v196, s[50:51] nt
	v_add_u32_e32 v196, 0x11200, v196
	global_load_dword v193, v196, s[50:51] nt
	v_add_u32_e32 v196, 0x11200, v196
	global_load_dword v194, v196, s[50:51] nt
	v_add_u32_e32 v196, 0x11200, v196
	global_load_dword v195, v196, s[50:51] nt
.Le17_wr:
	s_mov_b64 exec, s[6:7]
	s_waitcnt vmcnt(30)
	ds_write2_b32 v197, v164, v165 offset1:66
	s_waitcnt vmcnt(28)
	ds_write2_b32 v197, v166, v167 offset0:132 offset1:198
	v_add_u32_e32 v197, 0x420, v197
	s_waitcnt vmcnt(26)
	ds_write2_b32 v197, v168, v169 offset1:66
	s_waitcnt vmcnt(24)
	ds_write2_b32 v197, v170, v171 offset0:132 offset1:198
	v_add_u32_e32 v197, 0x420, v197
	s_waitcnt vmcnt(22)
	ds_write2_b32 v197, v172, v173 offset1:66
	s_waitcnt vmcnt(20)
	ds_write2_b32 v197, v174, v175 offset0:132 offset1:198
	v_add_u32_e32 v197, 0x420, v197
	s_waitcnt vmcnt(18)
	ds_write2_b32 v197, v176, v177 offset1:66
	s_waitcnt vmcnt(16)
	ds_write2_b32 v197, v178, v179 offset0:132 offset1:198
	v_add_u32_e32 v197, 0x420, v197
	s_waitcnt lgkmcnt(0)
	s_waitcnt vmcnt(14)
	ds_write2_b32 v197, v180, v181 offset1:66
	s_waitcnt vmcnt(12)
	ds_write2_b32 v197, v182, v183 offset0:132 offset1:198
	v_add_u32_e32 v197, 0x420, v197
	s_waitcnt vmcnt(10)
	ds_write2_b32 v197, v184, v185 offset1:66
	s_waitcnt vmcnt(8)
	ds_write2_b32 v197, v186, v187 offset0:132 offset1:198
	v_add_u32_e32 v197, 0x420, v197
	s_waitcnt vmcnt(6)
	ds_write2_b32 v197, v188, v189 offset1:66
	s_waitcnt vmcnt(4)
	ds_write2_b32 v197, v190, v191 offset0:132 offset1:198
	v_add_u32_e32 v197, 0x420, v197
	s_waitcnt vmcnt(2)
	ds_write2_b32 v197, v192, v193 offset1:66
	s_waitcnt vmcnt(0)
	ds_write2_b32 v197, v194, v195 offset0:132 offset1:198
	s_branch .Le17_rd

.LBB0_1376:
	s_ashr_i32 s0, s8, 31
	s_lshr_b32 s0, s0, 25
	s_add_i32 s0, s8, s0
	s_ashr_i32 s1, s0, 7
	s_lshl_b32 s0, s1, 6
	s_lshl_b32 s1, s1, 12
	s_sub_i32 s10, s9, s1
	v_add_u32_e32 v2, s10, v1
	s_lshl_b32 s4, s0, 14
	v_lshlrev_b32_e32 v196, 2, v2
	s_add_u32 s6, s82, s4
	v_lshl_add_u32 v196, v8, 14, v196
	s_addc_u32 s7, s83, 0
	v_mov_b32_e32 v197, v42
	global_load_dword v164, v196, s[6:7] nt
	v_add_u32_e32 v196, 0x8000, v196
	global_load_dword v165, v196, s[6:7] nt
	v_add_u32_e32 v196, 0x8000, v196
	global_load_dword v166, v196, s[6:7] nt
	v_add_u32_e32 v196, 0x8000, v196
	global_load_dword v167, v196, s[6:7] nt
	v_add_u32_e32 v196, 0x8000, v196
	global_load_dword v168, v196, s[6:7] nt
	v_add_u32_e32 v196, 0x8000, v196
	global_load_dword v169, v196, s[6:7] nt
	v_add_u32_e32 v196, 0x8000, v196
	global_load_dword v170, v196, s[6:7] nt
	v_add_u32_e32 v196, 0x8000, v196
	global_load_dword v171, v196, s[6:7] nt
	v_add_u32_e32 v196, 0x8000, v196
	global_load_dword v172, v196, s[6:7] nt
	v_add_u32_e32 v196, 0x8000, v196
	global_load_dword v173, v196, s[6:7] nt
	v_add_u32_e32 v196, 0x8000, v196
	global_load_dword v174, v196, s[6:7] nt
	v_add_u32_e32 v196, 0x8000, v196
	global_load_dword v175, v196, s[6:7] nt
	v_add_u32_e32 v196, 0x8000, v196
	global_load_dword v176, v196, s[6:7] nt
	v_add_u32_e32 v196, 0x8000, v196
	global_load_dword v177, v196, s[6:7] nt
	v_add_u32_e32 v196, 0x8000, v196
	global_load_dword v178, v196, s[6:7] nt
	v_add_u32_e32 v196, 0x8000, v196
	global_load_dword v179, v196, s[6:7] nt
	v_add_u32_e32 v196, 0x8000, v196
	global_load_dword v180, v196, s[6:7] nt
	v_add_u32_e32 v196, 0x8000, v196
	global_load_dword v181, v196, s[6:7] nt
	v_add_u32_e32 v196, 0x8000, v196
	global_load_dword v182, v196, s[6:7] nt
	v_add_u32_e32 v196, 0x8000, v196
	global_load_dword v183, v196, s[6:7] nt
	v_add_u32_e32 v196, 0x8000, v196
	global_load_dword v184, v196, s[6:7] nt
	v_add_u32_e32 v196, 0x8000, v196
	global_load_dword v185, v196, s[6:7] nt
	v_add_u32_e32 v196, 0x8000, v196
	global_load_dword v186, v196, s[6:7] nt
	v_add_u32_e32 v196, 0x8000, v196
	global_load_dword v187, v196, s[6:7] nt
	v_add_u32_e32 v196, 0x8000, v196
	global_load_dword v188, v196, s[6:7] nt
	v_add_u32_e32 v196, 0x8000, v196
	global_load_dword v189, v196, s[6:7] nt
	v_add_u32_e32 v196, 0x8000, v196
	global_load_dword v190, v196, s[6:7] nt
	v_add_u32_e32 v196, 0x8000, v196
	global_load_dword v191, v196, s[6:7] nt
	v_add_u32_e32 v196, 0x8000, v196
	global_load_dword v192, v196, s[6:7] nt
	v_add_u32_e32 v196, 0x8000, v196
	global_load_dword v193, v196, s[6:7] nt
	v_add_u32_e32 v196, 0x8000, v196
	global_load_dword v194, v196, s[6:7] nt
	v_add_u32_e32 v196, 0x8000, v196
	global_load_dword v195, v196, s[6:7] nt
	s_waitcnt vmcnt(30)
	ds_write2_b32 v197, v164, v165 offset1:66
	s_waitcnt vmcnt(28)
	ds_write2_b32 v197, v166, v167 offset0:132 offset1:198
	v_add_u32_e32 v197, 0x420, v197
	s_waitcnt vmcnt(26)
	ds_write2_b32 v197, v168, v169 offset1:66
	s_waitcnt vmcnt(24)
	ds_write2_b32 v197, v170, v171 offset0:132 offset1:198
	v_add_u32_e32 v197, 0x420, v197
	s_waitcnt vmcnt(22)
	ds_write2_b32 v197, v172, v173 offset1:66
	s_waitcnt vmcnt(20)
	ds_write2_b32 v197, v174, v175 offset0:132 offset1:198
	v_add_u32_e32 v197, 0x420, v197
	s_waitcnt vmcnt(18)
	ds_write2_b32 v197, v176, v177 offset1:66
	s_waitcnt vmcnt(16)
	ds_write2_b32 v197, v178, v179 offset0:132 offset1:198
	v_add_u32_e32 v197, 0x420, v197
	s_waitcnt lgkmcnt(0)
	s_waitcnt vmcnt(14)
	ds_write2_b32 v197, v180, v181 offset1:66
	s_waitcnt vmcnt(12)
	ds_write2_b32 v197, v182, v183 offset0:132 offset1:198
	v_add_u32_e32 v197, 0x420, v197
	s_waitcnt vmcnt(10)
	ds_write2_b32 v197, v184, v185 offset1:66
	s_waitcnt vmcnt(8)
	ds_write2_b32 v197, v186, v187 offset0:132 offset1:198
	v_add_u32_e32 v197, 0x420, v197
	s_waitcnt vmcnt(6)
	ds_write2_b32 v197, v188, v189 offset1:66
	s_waitcnt vmcnt(4)
	ds_write2_b32 v197, v190, v191 offset0:132 offset1:198
	v_add_u32_e32 v197, 0x420, v197
	s_waitcnt vmcnt(2)
	ds_write2_b32 v197, v192, v193 offset1:66
	s_waitcnt vmcnt(0)
	ds_write2_b32 v197, v194, v195 offset0:132 offset1:198
	s_branch .Le14_rd
.LBB0_1408:
	s_mov_b64 s[0:1], 0
